# GA loop: first query-column PV/row-sum MFMAs interleaved with the second column's exp2 stream (MFMA shadow filled with transcendental VALU); persistent ones operand
# speedup vs baseline: 1.0011x; 1.0011x over previous
.LBB0_1273:
	s_andn2_b64 vcc, exec, s[0:1]
	s_cbranch_vccnz .LBB0_1287
	s_lshl_b32 s0, s22, 1
	s_addk_i32 s0, 0xfeb0
	v_mov_b32_e32 v20, v201
	v_add_u32_e32 v8, s0, v149
	v_lshlrev_b32_e32 v0, 6, v8
	v_lshrrev_b32_e32 v6, 1, v20
	v_and_b32_e32 v2, 32, v6
	s_movk_i32 s0, 0xfc0
	v_ashrrev_i32_e32 v106, 7, v8
	v_bfe_u32 v5, v8, 6, 1
	v_and_or_b32 v0, v0, s0, v2
	v_mov_b64_e32 v[2:3], s[42:43]
	s_mov_b32 s0, 0x220000
	v_mad_i64_i32 v[2:3], s[0:1], v106, s0, v[2:3]
	v_lshlrev_b32_e32 v4, 7, v5
	v_and_or_b32 v110, v6, 64, v4
	v_mov_b64_e32 v[6:7], s[58:59]
	s_mov_b32 s0, 0x110000
	v_add_u32_e32 v108, 0x100, v0
	v_lshlrev_b32_e32 v0, 1, v110
	v_mad_i64_i32 v[6:7], s[0:1], v106, s0, v[6:7]
	v_and_b32_e32 v107, 15, v20
	v_bfe_u32 v21, v20, 4, 2
	v_lshl_add_u64 v[2:3], v[2:3], 0, v[0:1]
	v_lshlrev_b32_e32 v0, 6, v5
	v_mov_b32_e32 v5, v1
	s_movk_i32 s0, 0xff80
	v_lshl_add_u64 v[4:5], v[6:7], 0, v[4:5]
	v_and_or_b32 v6, v8, s0, v0
	v_or_b32_e32 v7, v108, v107
	v_lshlrev_b32_e32 v0, 4, v21
	v_lshl_add_u64 v[2:3], v[2:3], 0, v[0:1]
	v_lshlrev_b32_e32 v0, 9, v7
	v_lshl_add_u64 v[2:3], v[2:3], 0, v[0:1]
	s_movk_i32 s0, 0x2000
	global_load_dwordx4 v[46:49], v[2:3], off
	global_load_dwordx4 v[42:45], v[2:3], off offset:64
	v_add_co_u32_e32 v2, vcc, s0, v2
	v_and_b32_e32 v22, 7, v20
	s_nop 0
	v_addc_co_u32_e32 v3, vcc, 0, v3, vcc
	global_load_dwordx4 v[50:53], v[2:3], off
	global_load_dwordx4 v[54:57], v[2:3], off offset:64
	v_mov_b64_e32 v[2:3], s[44:45]
	v_bfe_u32 v126, v20, 3, 5
	v_lshlrev_b32_e32 v114, 4, v22
	v_mov_b32_e32 v115, v1
	v_mad_i64_i32 v[2:3], s[0:1], v6, s85, v[2:3]
	v_lshl_add_u64 v[116:117], v[4:5], 0, v[114:115]
	v_lshlrev_b32_e32 v0, 8, v126
	v_or_b32_e32 v23, 32, v126
	v_lshl_add_u64 v[18:19], v[2:3], 0, v[114:115]
	v_lshl_add_u64 v[2:3], v[116:117], 0, v[0:1]
	v_lshlrev_b32_e32 v0, 8, v23
	v_mad_u64_u32 v[6:7], s[0:1], v126, s85, v[18:19]
	v_lshl_add_u64 v[10:11], v[116:117], 0, v[0:1]
	v_mad_u64_u32 v[14:15], s[0:1], v23, s85, v[18:19]
	v_mov_b32 v122, 0xc2800000
	global_load_dwordx4 v[2:5], v[2:3], off
	s_nop 0
	global_load_dwordx4 v[6:9], v[6:7], off
	s_nop 0
	global_load_dwordx4 v[10:13], v[10:11], off
	s_nop 0
	global_load_dwordx4 v[14:17], v[14:15], off
	v_lshrrev_b32_e32 v26, 3, v20
	v_lshrrev_b32_e32 v25, 4, v20
	v_xor_b32_e32 v20, v26, v20
	v_lshlrev_b32_e32 v20, 4, v20
	v_and_b32_e32 v132, 0x70, v20
	v_lshlrev_b32_e32 v112, 3, v21
	v_lshlrev_b32_e32 v127, 7, v126
	v_bitop3_b32 v21, v21, v22, 4 bitop3:0x36
	v_add_u32_e32 v20, v150, v132
	v_and_b32_e32 v24, 64, v208
	v_mul_u32_u24_e32 v128, 0x90, v126
	v_lshlrev_b32_e32 v131, 7, v23
	v_lshlrev_b32_e32 v129, 4, v21
	v_add_u32_e32 v21, v20, v127
	v_xor_b32_e32 v0, 16, v208
	v_bitop3_b32 v25, v25, v22, 3 bitop3:0x6c
	v_add3_u32 v22, v150, v114, v128
	v_add_u32_e32 v20, v20, v131
	v_lshlrev_b32_e32 v130, 4, v25
	v_mov_b32_e32 v38, 0
	s_mov_b32 s0, 0
	v_lshlrev_b32_e32 v115, 7, v107
	v_mov_b32_e32 v123, v122
	v_mov_b32_e32 v165, 0
	v_mov_b32_e32 v152, 0x42800000
	v_mov_b32_e32 v153, v152
	v_mov_b32_e32 v154, v152
	v_mov_b32_e32 v155, v152
	v_mov_b32_e32 v156, v152
	v_mov_b32_e32 v157, v152
	v_mov_b32_e32 v158, v152
	v_mov_b32_e32 v159, v152
	v_mul_u32_u24_e32 v109, 0x90, v107
	v_mov_b32_e32 v39, v38
	v_mov_b32_e32 v40, v38
	v_mov_b32_e32 v41, v38
	v_mov_b32_e32 v34, v38
	v_mov_b32_e32 v35, v38
	v_mov_b32_e32 v36, v38
	v_mov_b32_e32 v37, v38
	s_waitcnt vmcnt(0) lgkmcnt(0)
	ds_write_b128 v21, v[2:5]
	ds_write_b128 v22, v[6:9] offset:8192
	ds_write_b128 v20, v[10:13]
	ds_write_b128 v22, v[14:17] offset:12800
	v_add_u32_e32 v2, 64, v24
	v_cmp_lt_i32_e32 vcc, v0, v2
	v_mov_b32_e32 v3, v1
	s_waitcnt lgkmcnt(0)
	v_cndmask_b32_e32 v0, v208, v0, vcc
	v_lshlrev_b32_e32 v111, 2, v0
	v_xor_b32_e32 v0, 32, v208
	v_cmp_lt_i32_e32 vcc, v0, v2
	v_mov_b32_e32 v2, v1
	s_barrier
	v_cndmask_b32_e32 v0, v208, v0, vcc
	v_lshlrev_b32_e32 v113, 2, v0
	v_mul_u32_u24_e32 v0, 0x1100, v126
	v_lshlrev_b32_e32 v0, 1, v0
	v_lshl_add_u64 v[120:121], v[18:19], 0, v[0:1]
	v_mov_b32_e32 v0, v1
	v_mov_b64_e32 v[20:21], v[2:3]
	v_mov_b64_e32 v[24:25], v[2:3]
	v_mov_b64_e32 v[28:29], v[2:3]
	v_mov_b64_e32 v[32:33], v[2:3]
	v_mov_b64_e32 v[12:13], v[2:3]
	v_mov_b64_e32 v[16:17], v[2:3]
	v_mov_b64_e32 v[8:9], v[2:3]
	v_mov_b64_e32 v[18:19], v[0:1]
	v_mov_b64_e32 v[22:23], v[0:1]
	v_mov_b64_e32 v[26:27], v[0:1]
	v_mov_b64_e32 v[30:31], v[0:1]
	v_mov_b64_e32 v[10:11], v[0:1]
	v_mov_b64_e32 v[14:15], v[0:1]
	v_mov_b64_e32 v[6:7], v[0:1]
	v_mov_b64_e32 v[4:5], v[2:3]
	v_mov_b64_e32 v[2:3], v[0:1]
	v_add_u32_e32 v170, v150, v115
	v_add_u32_e32 v171, v170, v129
	v_add_u32_e32 v170, v170, v130
	v_add3_u32 v172, v150, v109, v112
	v_add_u32_e32 v173, 0x2800, v172
	v_add_u32_e32 v174, 0x6400, v172
	v_add_u32_e32 v175, 0x6c00, v172
	v_add_u32_e32 v176, 0x3000, v172
	v_add_u32_e32 v177, 0x3800, v172
	v_add_u32_e32 v178, 0x7400, v172
	v_add_u32_e32 v179, 0x7c00, v172
	v_add_u32_e32 v172, 0x2000, v172
	v_add_u32_e32 v180, v150, v132
	v_add_u32_e32 v181, v180, v131
	v_add_u32_e32 v180, v180, v127
	v_add3_u32 v182, v150, v114, v128
	v_lshlrev_b32_e32 v164, 8, v126
	v_lshl_add_u64 v[184:185], v[116:117], 0, v[164:165]
	s_mov_b64 s[2:3], 0x2000
	v_lshl_add_u64 v[186:187], v[184:185], 0, s[2:3]
	s_mov_b64 s[2:3], 0x44000
	v_lshl_add_u64 v[188:189], v[120:121], 0, s[2:3]
	v_mov_b32_e32 v190, s36
	v_mov_b32_e32 v191, s36
	v_mov_b32_e32 v192, s36
	v_mov_b32_e32 v193, s36
	s_mov_b32 s1, 1
	v_lshl_or_b32 v68, s1, 6, v126
	v_lshlrev_b32_e32 v0, 8, v68
	s_lshl_b32 s56, s1, 7
	v_lshl_add_u64 v[58:59], v[116:117], 0, v[0:1]
	v_lshl_add_u64 v[66:67], v[120:121], 0, s[56:57]
	v_or_b32_e32 v0, 32, v68
	s_mov_b32 s1, 0x44000
	v_lshlrev_b64 v[68:69], 8, v[0:1]
	v_add_co_u32_e32 v70, vcc, s1, v66
	v_lshl_add_u64 v[68:69], v[116:117], 0, v[68:69]
	s_nop 0
	v_addc_co_u32_e32 v71, vcc, 0, v67, vcc
	global_load_dwordx4 v[58:61], v[58:59], off
	s_nop 0
	global_load_dwordx4 v[62:65], v[66:67], off
	s_nop 0
	global_load_dwordx4 v[66:69], v[68:69], off
	s_nop 0
	global_load_dwordx4 v[70:73], v[70:71], off

.LBB0_1280:
	v_mov_b64_e32 v[118:119], v[124:125]
	v_exp_f32_e32 v94, v94
	v_exp_f32_e32 v95, v95
	v_exp_f32_e32 v96, v96
	v_exp_f32_e32 v97, v97
	v_exp_f32_e32 v90, v90
	v_exp_f32_e32 v91, v91
	v_exp_f32_e32 v92, v92
	v_exp_f32_e32 v93, v93
	v_exp_f32_e32 v102, v102
	v_exp_f32_e32 v103, v103
	v_exp_f32_e32 v104, v104
	v_exp_f32_e32 v105, v105
	v_exp_f32_e32 v98, v98
	v_exp_f32_e32 v99, v99
	v_exp_f32_e32 v100, v100
	v_exp_f32_e32 v101, v101
	v_cvt_pk_bf16_f32 v160, v94, v95
	v_cvt_pk_bf16_f32 v161, v96, v97
	v_cvt_pk_bf16_f32 v162, v90, v91
	v_cvt_pk_bf16_f32 v163, v92, v93
	v_cvt_pk_bf16_f32 v166, v102, v103
	v_cvt_pk_bf16_f32 v167, v104, v105
	v_cvt_pk_bf16_f32 v168, v98, v99
	v_cvt_pk_bf16_f32 v169, v100, v101
	s_setprio 1
	s_waitcnt vmcnt(4)
	ds_write_b128 v180, v[58:61] offset:17408
	ds_write_b128 v182, v[62:65] offset:25600
	ds_write_b128 v181, v[66:69] offset:17408
	ds_write_b128 v182, v[70:73] offset:30208
	ds_read2_b64 v[94:97], v176 offset0:64 offset1:68
	ds_read2_b64 v[98:101], v176 offset0:72 offset1:76
	ds_read2_b64 v[102:105], v177 offset0:96 offset1:100
	v_mfma_f32_16x16x32_bf16 v[38:41], v[190:193], v[160:163], v[38:41]
	v_exp_f32_e32 v134, v74
	v_exp_f32_e32 v135, v75
	v_mfma_f32_16x16x32_bf16 v[38:41], v[190:193], v[166:169], v[38:41]
	v_exp_f32_e32 v136, v76
	v_exp_f32_e32 v137, v77
	v_mfma_f32_16x16x32_bf16 v[30:33], v[212:215], v[160:163], v[30:33]
	v_exp_f32_e32 v138, v86
	v_exp_f32_e32 v139, v87
	v_mfma_f32_16x16x32_bf16 v[22:25], v[244:247], v[160:163], v[22:25]
	v_exp_f32_e32 v140, v88
	v_exp_f32_e32 v141, v89
	v_mfma_f32_16x16x32_bf16 v[30:33], v[216:219], v[166:169], v[30:33]
	v_exp_f32_e32 v122, v78
	v_exp_f32_e32 v123, v79
	v_mfma_f32_16x16x32_bf16 v[22:25], v[248:251], v[166:169], v[22:25]
	v_exp_f32_e32 v124, v80
	v_exp_f32_e32 v133, v81
	s_waitcnt lgkmcnt(0)
	v_mfma_f32_16x16x32_bf16 v[10:13], v[94:97], v[160:163], v[10:13]
	v_exp_f32_e32 v142, v82
	v_exp_f32_e32 v143, v83
	v_mfma_f32_16x16x32_bf16 v[6:9], v[102:105], v[160:163], v[6:9]
	v_exp_f32_e32 v144, v84
	v_exp_f32_e32 v125, v85
	v_mfma_f32_16x16x32_bf16 v[10:13], v[98:101], v[166:169], v[10:13]
	v_cvt_pk_bf16_f32 v88, v134, v135
	v_cvt_pk_bf16_f32 v89, v136, v137
	ds_read2_b64 v[134:137], v177 offset0:104 offset1:108
	v_cvt_pk_bf16_f32 v90, v138, v139
	v_cvt_pk_bf16_f32 v91, v140, v141
	v_cvt_pk_bf16_f32 v92, v142, v143
	v_cvt_pk_bf16_f32 v93, v144, v125
	v_cvt_pk_bf16_f32 v86, v122, v123
	v_cvt_pk_bf16_f32 v87, v124, v133
	s_nop 1
	v_mfma_f32_16x16x32_bf16 v[34:37], v[190:193], v[86:89], v[34:37]
	v_mfma_f32_16x16x32_bf16 v[34:37], v[190:193], v[90:93], v[34:37]
	v_mfma_f32_16x16x32_bf16 v[26:29], v[212:215], v[86:89], v[26:29]
	v_mfma_f32_16x16x32_bf16 v[18:21], v[244:247], v[86:89], v[18:21]
	v_mfma_f32_16x16x32_bf16 v[26:29], v[216:219], v[90:93], v[26:29]
	v_mfma_f32_16x16x32_bf16 v[18:21], v[248:251], v[90:93], v[18:21]
	v_mfma_f32_16x16x32_bf16 v[14:17], v[94:97], v[86:89], v[14:17]
	v_mfma_f32_16x16x32_bf16 v[2:5], v[102:105], v[86:89], v[2:5]
	v_mfma_f32_16x16x32_bf16 v[14:17], v[98:101], v[90:93], v[14:17]
	s_waitcnt lgkmcnt(0)
	v_mfma_f32_16x16x32_bf16 v[6:9], v[134:137], v[166:169], v[6:9]
	v_mfma_f32_16x16x32_bf16 v[2:5], v[134:137], v[90:93], v[2:5]
	s_setprio 0
	s_cmpk_lg_i32 s0, 0x43
	s_waitcnt lgkmcnt(0)
	s_barrier
	s_cbranch_scc0 .LBB0_1282
	v_mov_b64_e32 v[122:123], v[118:119]
	s_branch .Lga_odd

.Lga_o_1280:
	v_mov_b64_e32 v[118:119], v[124:125]
	v_exp_f32_e32 v94, v94
	v_exp_f32_e32 v95, v95
	v_exp_f32_e32 v96, v96
	v_exp_f32_e32 v97, v97
	v_exp_f32_e32 v90, v90
	v_exp_f32_e32 v91, v91
	v_exp_f32_e32 v92, v92
	v_exp_f32_e32 v93, v93
	v_exp_f32_e32 v102, v102
	v_exp_f32_e32 v103, v103
	v_exp_f32_e32 v104, v104
	v_exp_f32_e32 v105, v105
	v_exp_f32_e32 v98, v98
	v_exp_f32_e32 v99, v99
	v_exp_f32_e32 v100, v100
	v_exp_f32_e32 v101, v101
	v_cvt_pk_bf16_f32 v160, v94, v95
	v_cvt_pk_bf16_f32 v161, v96, v97
	v_cvt_pk_bf16_f32 v162, v90, v91
	v_cvt_pk_bf16_f32 v163, v92, v93
	v_cvt_pk_bf16_f32 v166, v102, v103
	v_cvt_pk_bf16_f32 v167, v104, v105
	v_cvt_pk_bf16_f32 v168, v98, v99
	v_cvt_pk_bf16_f32 v169, v100, v101
	s_setprio 1
	s_waitcnt vmcnt(4)
	ds_write_b128 v180, v[228:231]
	ds_write_b128 v182, v[232:235] offset:8192
	ds_write_b128 v181, v[236:239]
	ds_write_b128 v182, v[240:243] offset:12800
	ds_read2_b64 v[94:97], v178 offset0:64 offset1:68
	ds_read2_b64 v[98:101], v178 offset0:72 offset1:76
	ds_read2_b64 v[102:105], v179 offset0:96 offset1:100
	v_mfma_f32_16x16x32_bf16 v[38:41], v[190:193], v[160:163], v[38:41]
	v_exp_f32_e32 v134, v74
	v_exp_f32_e32 v135, v75
	v_mfma_f32_16x16x32_bf16 v[38:41], v[190:193], v[166:169], v[38:41]
	v_exp_f32_e32 v136, v76
	v_exp_f32_e32 v137, v77
	v_mfma_f32_16x16x32_bf16 v[30:33], v[212:215], v[160:163], v[30:33]
	v_exp_f32_e32 v138, v86
	v_exp_f32_e32 v139, v87
	v_mfma_f32_16x16x32_bf16 v[22:25], v[244:247], v[160:163], v[22:25]
	v_exp_f32_e32 v140, v88
	v_exp_f32_e32 v141, v89
	v_mfma_f32_16x16x32_bf16 v[30:33], v[216:219], v[166:169], v[30:33]
	v_exp_f32_e32 v122, v78
	v_exp_f32_e32 v123, v79
	v_mfma_f32_16x16x32_bf16 v[22:25], v[248:251], v[166:169], v[22:25]
	v_exp_f32_e32 v124, v80
	v_exp_f32_e32 v133, v81
	s_waitcnt lgkmcnt(0)
	v_mfma_f32_16x16x32_bf16 v[10:13], v[94:97], v[160:163], v[10:13]
	v_exp_f32_e32 v142, v82
	v_exp_f32_e32 v143, v83
	v_mfma_f32_16x16x32_bf16 v[6:9], v[102:105], v[160:163], v[6:9]
	v_exp_f32_e32 v144, v84
	v_exp_f32_e32 v125, v85
	v_mfma_f32_16x16x32_bf16 v[10:13], v[98:101], v[166:169], v[10:13]
	v_cvt_pk_bf16_f32 v88, v134, v135
	v_cvt_pk_bf16_f32 v89, v136, v137
	ds_read2_b64 v[134:137], v179 offset0:104 offset1:108
	v_cvt_pk_bf16_f32 v90, v138, v139
	v_cvt_pk_bf16_f32 v91, v140, v141
	v_cvt_pk_bf16_f32 v92, v142, v143
	v_cvt_pk_bf16_f32 v93, v144, v125
	v_cvt_pk_bf16_f32 v86, v122, v123
	v_cvt_pk_bf16_f32 v87, v124, v133
	s_nop 1
	v_mfma_f32_16x16x32_bf16 v[34:37], v[190:193], v[86:89], v[34:37]
	v_mfma_f32_16x16x32_bf16 v[34:37], v[190:193], v[90:93], v[34:37]
	v_mfma_f32_16x16x32_bf16 v[26:29], v[212:215], v[86:89], v[26:29]
	v_mfma_f32_16x16x32_bf16 v[18:21], v[244:247], v[86:89], v[18:21]
	v_mfma_f32_16x16x32_bf16 v[26:29], v[216:219], v[90:93], v[26:29]
	v_mfma_f32_16x16x32_bf16 v[18:21], v[248:251], v[90:93], v[18:21]
	v_mfma_f32_16x16x32_bf16 v[14:17], v[94:97], v[86:89], v[14:17]
	v_mfma_f32_16x16x32_bf16 v[2:5], v[102:105], v[86:89], v[2:5]
	v_mfma_f32_16x16x32_bf16 v[14:17], v[98:101], v[90:93], v[14:17]
	s_waitcnt lgkmcnt(0)
	v_mfma_f32_16x16x32_bf16 v[6:9], v[134:137], v[166:169], v[6:9]
	v_mfma_f32_16x16x32_bf16 v[2:5], v[134:137], v[90:93], v[2:5]
	s_setprio 0
	s_cmpk_lg_i32 s0, 0x43
	s_waitcnt lgkmcnt(0)
	s_barrier
	s_cbranch_scc0 .LBB0_1282
	v_mov_b64_e32 v[122:123], v[118:119]
	s_branch .LBB0_1275
